# instruction selection (7.5): 30 v_pk_mul_f32 between MFMAs in hgrn_s1 split into scalar v_mul_f32 pairs, on top of noprio+nonop
# speedup vs baseline: 1.0170x; 1.0043x over previous
; #define LAS __attribute__((address_space(3)))
; #define LBAR() do { asm volatile("s_waitcnt lgkmcnt(0)" ::: "memory"); __builtin_amdgcn_s_barrier(); asm volatile("" ::: "memory"); } while (0)
; #define MFMA16(a, b, c) __builtin_amdgcn_mfma_f32_16x16x32_bf16((b), (a), (c), 0, 0, 0)
; __device__ __forceinline__ void hgrn_s1(Frame& F) {
;     ...
;             LAS float* DL = (LAS float*)(lds + T_DL) + par * 256;
;             if (tq == 0) { DL[k] = __builtin_amdgcn_exp2f(totf); }
;             if (tq == 1) { F_DEC[(size_t)((bh * 2 + 1) * 256 + cb) * 128 + k] = __builtin_amdgcn_exp2f(cumb); DL[128 + k] = __builtin_amdgcn_exp2f(totb); }
;             cumf += totf; cumb += totb;
;             LBAR();
; #pragma unroll
;             for (int dir = 0; dir < 2; ++dir) {
;                 const LAS unsigned char* kt = lds + T_KT + (par * 2 + dir) * 128 * P64;
;                 const bf16x8 a0 = dir ? a0b : a0f, a1 = dir ? a1b : a1f;
; #pragma unroll
;                 for (int gg = 0; gg < 4; ++gg) {
;                     f32x4 r0 = dir ? Rb[gg][0] : Rf[gg][0], r1 = dir ? Rb[gg][1] : Rf[gg][1];
;                     const f32x4 d0 = *(const LAS f32x4*)(DL + dir * 128 + 32 * gg + 8 * fq), d1 = *(const LAS f32x4*)(DL + dir * 128 + 32 * gg + 8 * fq + 4);
;                     r0 = r0 * d0; r1 = r1 * d1;
;                     r0 = MFMA16(a0, ldfrag(kt, P64, 32 * gg + fr, fq * 16), r0);
;                     r1 = MFMA16(a0, ldfrag(kt, P64, 32 * gg + 16 + fr, fq * 16), r1);
;                     r0 = MFMA16(a1, ldfrag(kt, P64, 32 * gg + fr, 64 + fq * 16), r0);
;                     r1 = MFMA16(a1, ldfrag(kt, P64, 32 * gg + 16 + fr, 64 + fq * 16), r1);
;                     if (dir) { Rb[gg][0] = r0; Rb[gg][1] = r1; } else { Rf[gg][0] = r0; Rf[gg][1] = r1; }
;                 }
;             }
.LBB0_339:
	s_or_b64 exec, exec, s[30:31]
	s_waitcnt lgkmcnt(0)
	s_barrier
	v_add3_u32 v127, s56, v172, v134
	v_lshl_add_u32 v126, v132, 2, s57
	ds_read_b128 v[114:117], v127
	ds_read_b128 v[118:121], v126
	ds_read_b128 v[122:125], v127 offset:2304
	ds_read_b128 v[158:161], v126 offset:16
	s_add_i32 s55, s55, 1
	s_add_i32 s39, s39, -1
	s_waitcnt lgkmcnt(2)
	v_pk_mul_f32 v[50:51], v[50:51], v[120:121]
	v_pk_mul_f32 v[48:49], v[48:49], v[118:119]
	ds_read_b128 v[118:121], v127 offset:64
	s_waitcnt lgkmcnt(1)
	v_mul_f32_e32 v70, v70, v160
	v_mul_f32_e32 v71, v71, v161
	v_mfma_f32_16x16x32_bf16 v[48:51], v[114:117], v[108:111], v[48:51]
	ds_read_b128 v[114:117], v127 offset:2368
	v_mul_f32_e32 v68, v68, v158
	v_mul_f32_e32 v69, v69, v159
	v_pk_add_f32 v[152:153], v[152:153], v[112:113]
	s_waitcnt lgkmcnt(1)
	v_mfma_f32_16x16x32_bf16 v[48:51], v[118:121], v[104:107], v[48:51]
	v_lshl_add_u64 v[154:155], v[154:155], 0, s[26:27]
	v_lshl_add_u64 v[156:157], v[156:157], 0, s[28:29]
	s_cmp_eq_u32 s55, 16
	v_mfma_f32_16x16x32_bf16 v[68:71], v[122:125], v[108:111], v[68:71]
	ds_read_b128 v[118:121], v127 offset:4608
	ds_read_b128 v[122:125], v126 offset:128
	s_waitcnt lgkmcnt(0)
	v_mul_f32_e32 v46, v46, v124
	v_mul_f32_e32 v47, v47, v125
	v_mfma_f32_16x16x32_bf16 v[68:71], v[114:117], v[104:107], v[68:71]
	ds_read_b128 v[114:117], v127 offset:6912
	ds_read_b128 v[158:161], v126 offset:144
	v_mul_f32_e32 v44, v44, v122
	v_mul_f32_e32 v45, v45, v123
	ds_read_b128 v[122:125], v127 offset:4672
	s_waitcnt lgkmcnt(1)
	v_mul_f32_e32 v62, v62, v160
	v_mul_f32_e32 v63, v63, v161
	v_mfma_f32_16x16x32_bf16 v[44:47], v[118:121], v[108:111], v[44:47]
	ds_read_b128 v[118:121], v127 offset:6976
	v_mul_f32_e32 v60, v60, v158
	v_mul_f32_e32 v61, v61, v159
	s_waitcnt lgkmcnt(1)
	v_mfma_f32_16x16x32_bf16 v[44:47], v[122:125], v[104:107], v[44:47]
	v_mfma_f32_16x16x32_bf16 v[60:63], v[114:117], v[108:111], v[60:63]
	ds_read_b128 v[114:117], v127 offset:9216
	ds_read_b128 v[122:125], v126 offset:256
	s_waitcnt lgkmcnt(0)
	v_mul_f32_e32 v42, v42, v124
	v_mul_f32_e32 v43, v43, v125
	v_mfma_f32_16x16x32_bf16 v[60:63], v[118:121], v[104:107], v[60:63]
	ds_read_b128 v[118:121], v127 offset:11520
	ds_read_b128 v[158:161], v126 offset:272
	v_mul_f32_e32 v40, v40, v122
	v_mul_f32_e32 v41, v41, v123
	ds_read_b128 v[122:125], v127 offset:9280
	s_waitcnt lgkmcnt(1)
	v_mul_f32_e32 v58, v58, v160
	v_mul_f32_e32 v59, v59, v161
	v_mfma_f32_16x16x32_bf16 v[40:43], v[114:117], v[108:111], v[40:43]
	ds_read_b128 v[114:117], v127 offset:11584
	v_mul_f32_e32 v56, v56, v158
	v_mul_f32_e32 v57, v57, v159
	s_waitcnt lgkmcnt(1)
	v_mfma_f32_16x16x32_bf16 v[40:43], v[122:125], v[104:107], v[40:43]
	v_mfma_f32_16x16x32_bf16 v[56:59], v[118:121], v[108:111], v[56:59]
	ds_read_b128 v[118:121], v127 offset:13824
	ds_read_b128 v[122:125], v126 offset:384
	s_waitcnt lgkmcnt(0)
	v_mul_f32_e32 v38, v38, v124
	v_mul_f32_e32 v39, v39, v125
	v_mfma_f32_16x16x32_bf16 v[56:59], v[114:117], v[104:107], v[56:59]
	ds_read_b128 v[114:117], v127 offset:16128
	ds_read_b128 v[158:161], v126 offset:400
	v_mul_f32_e32 v36, v36, v122
	v_mul_f32_e32 v37, v37, v123
	ds_read_b128 v[122:125], v127 offset:13888
	s_waitcnt lgkmcnt(1)
	v_mul_f32_e32 v54, v54, v160
	v_mul_f32_e32 v55, v55, v161
	v_mfma_f32_16x16x32_bf16 v[36:39], v[118:121], v[108:111], v[36:39]
	ds_read_b128 v[118:121], v127 offset:16192
	v_mul_f32_e32 v52, v52, v158
	v_mul_f32_e32 v53, v53, v159
	s_waitcnt lgkmcnt(1)
	v_mfma_f32_16x16x32_bf16 v[36:39], v[122:125], v[104:107], v[36:39]
	v_mfma_f32_16x16x32_bf16 v[52:55], v[114:117], v[108:111], v[52:55]
	ds_read_b128 v[108:111], v127 offset:18432
	ds_read_b128 v[114:117], v126 offset:512
	s_waitcnt lgkmcnt(0)
	v_mul_f32_e32 v10, v10, v116
	v_mul_f32_e32 v11, v11, v117
	v_mfma_f32_16x16x32_bf16 v[52:55], v[118:121], v[104:107], v[52:55]
	ds_read_b128 v[104:107], v127 offset:20736
	ds_read_b128 v[118:121], v126 offset:528
	v_mul_f32_e32 v8, v8, v114
	v_mul_f32_e32 v9, v9, v115
	ds_read_b128 v[114:117], v127 offset:18496
	s_waitcnt lgkmcnt(1)
	v_mul_f32_e32 v22, v22, v120
	v_mul_f32_e32 v23, v23, v121
	v_mfma_f32_16x16x32_bf16 v[8:11], v[108:111], v[64:67], v[8:11]
	ds_read_b128 v[108:111], v127 offset:20800
	v_mul_f32_e32 v20, v20, v118
	v_mul_f32_e32 v21, v21, v119
	s_waitcnt lgkmcnt(1)
	v_mfma_f32_16x16x32_bf16 v[8:11], v[114:117], v[28:31], v[8:11]
	v_mfma_f32_16x16x32_bf16 v[20:23], v[104:107], v[64:67], v[20:23]
	ds_read_b128 v[104:107], v127 offset:23040
	ds_read_b128 v[114:117], v126 offset:640
	s_waitcnt lgkmcnt(0)
	v_mul_f32_e32 v6, v6, v116
	v_mul_f32_e32 v7, v7, v117
	v_mfma_f32_16x16x32_bf16 v[20:23], v[108:111], v[28:31], v[20:23]
	ds_read_b128 v[108:111], v127 offset:25344
	ds_read_b128 v[118:121], v126 offset:656
	v_mul_f32_e32 v4, v4, v114
	v_mul_f32_e32 v5, v5, v115
	ds_read_b128 v[114:117], v127 offset:23104
	s_waitcnt lgkmcnt(1)
	v_mul_f32_e32 v18, v18, v120
	v_mul_f32_e32 v19, v19, v121
	v_mfma_f32_16x16x32_bf16 v[4:7], v[104:107], v[64:67], v[4:7]
	ds_read_b128 v[104:107], v127 offset:25408
	v_mul_f32_e32 v16, v16, v118
	v_mul_f32_e32 v17, v17, v119
	s_waitcnt lgkmcnt(1)
	v_mfma_f32_16x16x32_bf16 v[4:7], v[114:117], v[28:31], v[4:7]
	v_mfma_f32_16x16x32_bf16 v[16:19], v[108:111], v[64:67], v[16:19]
	ds_read_b128 v[108:111], v127 offset:27648
	ds_read_b128 v[114:117], v126 offset:768
	s_waitcnt lgkmcnt(0)
	v_mul_f32_e32 v2, v2, v116
	v_mul_f32_e32 v3, v3, v117
	v_mfma_f32_16x16x32_bf16 v[16:19], v[104:107], v[28:31], v[16:19]
	ds_read_b128 v[104:107], v127 offset:29952
	ds_read_b128 v[118:121], v126 offset:784
	v_mul_f32_e32 v0, v0, v114
	v_mul_f32_e32 v1, v1, v115
	ds_read_b128 v[114:117], v127 offset:27712
	s_waitcnt lgkmcnt(1)
	v_mul_f32_e32 v26, v26, v120
	v_mul_f32_e32 v27, v27, v121
	v_mfma_f32_16x16x32_bf16 v[0:3], v[108:111], v[64:67], v[0:3]
	ds_read_b128 v[108:111], v127 offset:30016
	v_mul_f32_e32 v24, v24, v118
	v_mul_f32_e32 v25, v25, v119
	s_waitcnt lgkmcnt(1)
	v_mfma_f32_16x16x32_bf16 v[0:3], v[114:117], v[28:31], v[0:3]
	v_mfma_f32_16x16x32_bf16 v[24:27], v[104:107], v[64:67], v[24:27]
	ds_read_b128 v[104:107], v127 offset:32256
	ds_read_b128 v[114:117], v126 offset:896
	ds_read_b128 v[118:121], v127 offset:34560
	s_waitcnt lgkmcnt(1)
	v_mul_f32_e32 v14, v14, v116
	v_mul_f32_e32 v15, v15, v117
	v_mfma_f32_16x16x32_bf16 v[24:27], v[108:111], v[28:31], v[24:27]
	ds_read_b128 v[108:111], v126 offset:912
	v_mul_f32_e32 v12, v12, v114
	v_mul_f32_e32 v13, v13, v115
	ds_read_b128 v[114:117], v127 offset:32320
	s_nop 0
	v_mfma_f32_16x16x32_bf16 v[12:15], v[104:107], v[64:67], v[12:15]
	ds_read_b128 v[104:107], v127 offset:34624
	s_waitcnt lgkmcnt(2)
	v_mul_f32_e32 v34, v34, v110
	v_mul_f32_e32 v35, v35, v111
	v_mul_f32_e32 v32, v32, v108
	v_mul_f32_e32 v33, v33, v109
	s_waitcnt lgkmcnt(1)
	v_mfma_f32_16x16x32_bf16 v[12:15], v[114:117], v[28:31], v[12:15]
	v_mfma_f32_16x16x32_bf16 v[32:35], v[118:121], v[64:67], v[32:35]
	s_waitcnt lgkmcnt(0)
	v_mfma_f32_16x16x32_bf16 v[32:35], v[104:107], v[28:31], v[32:35]
	s_cbranch_scc1 .LBB0_341
	s_waitcnt vmcnt(2)
	v_mov_b64_e32 v[106:107], v[94:95]
	v_mov_b64_e32 v[110:111], v[90:91]
	s_waitcnt vmcnt(0)
	v_mov_b64_e32 v[28:29], v[100:101]
	v_mov_b64_e32 v[64:65], v[96:97]
	v_mov_b64_e32 v[118:119], v[86:87]
	v_mov_b64_e32 v[114:115], v[82:83]
	v_mov_b64_e32 v[122:123], v[78:79]
	v_mov_b64_e32 v[126:127], v[74:75]
	v_mov_b64_e32 v[104:105], v[92:93]
	v_mov_b64_e32 v[108:109], v[88:89]
	v_mov_b64_e32 v[30:31], v[102:103]
	v_mov_b64_e32 v[66:67], v[98:99]
	v_mov_b64_e32 v[116:117], v[84:85]
	v_mov_b64_e32 v[112:113], v[80:81]
	v_mov_b64_e32 v[120:121], v[76:77]
	v_mov_b64_e32 v[124:125], v[72:73]
	s_branch .LBB0_331
